# A gate-tile epilogue: drop redundant canonicalizing v_max before v_med3 clamp (128 VALU per gate unit per wave)
# speedup vs baseline: 1.0047x; 1.0011x over previous
.LBB0_434:
	s_cmp_gt_u32 s50, 9
	s_cselect_b64 s[24:25], -1, 0
	s_cmp_gt_u32 s50, 7
	s_cselect_b64 s[8:9], -1, 0
	s_and_b64 s[10:11], s[8:9], exec
	s_cselect_b32 s14, 0x840000, 0
	s_lshl_b32 s15, s4, 2
	s_cmp_lt_i32 s44, 2
	s_cselect_b64 s[76:77], -1, 0
	s_cmp_lt_u32 s50, 2
	v_mov_b32_e32 v200, v198
	v_mov_b32_e32 v201, v198
	s_cselect_b64 s[42:43], -1, 0
	s_cmp_gt_i32 s50, 5
	v_pk_fma_f32 v[178:179], v[130:131], v[200:201], v[178:179]
	v_or_b32_e32 v200, s53, v1
	v_or_b32_e32 v14, 0xfffffb00, v207
	s_cselect_b64 s[92:93], -1, 0
	v_pk_fma_f32 v[176:177], v[128:129], v[198:199], v[176:177]
	v_ashrrev_i32_e32 v201, 31, v200
	v_lshl_add_u32 v14, s50, 7, v14
	v_cmp_ne_u64_e64 s[38:39], 0, v[194:195]
	s_mov_b64 s[10:11], -1
	s_and_b64 vcc, exec, s[92:93]
	s_cbranch_vccz .LBB0_444
	s_andn2_b64 vcc, exec, s[24:25]
	s_cbranch_vccnz .LBB0_437
	s_nop 0
	s_mov_b32 s4, 0xc22c0000
	v_med3_f32 v198, v176, s4, v236
	v_exp_f32_e32 v198, v198
	s_nop 0
	v_med3_f32 v199, v168, s4, v236
	s_nop 0
	s_nop 0
	v_exp_f32_e32 v199, v199
	v_add_f32_e32 v198, 1.0, v198
	v_med3_f32 v205, v169, s4, v236
	v_med3_f32 v204, v177, s4, v236
	v_rcp_f32_e32 v198, v198
	v_exp_f32_e32 v205, v205
	v_exp_f32_e32 v204, v204
	v_add_f32_e32 v199, 1.0, v199
	s_nop 0
	v_rcp_f32_e32 v217, v199
	v_mul_f32_e32 v198, v199, v198
	v_add_f32_e32 v199, 1.0, v205
	v_add_f32_e32 v204, 1.0, v204
	s_nop 0
	v_med3_f32 v218, v170, s4, v236
	v_rcp_f32_e32 v204, v204
	v_exp_f32_e32 v218, v218
	v_med3_f32 v205, v178, s4, v236
	v_exp_f32_e32 v205, v205
	v_rcp_f32_e32 v224, v199
	v_mul_f32_e32 v199, v199, v204
	v_add_f32_e32 v204, 1.0, v218
	s_nop 0
	s_nop 0
	v_add_f32_e32 v205, 1.0, v205
	v_med3_f32 v219, v171, s4, v236
	v_med3_f32 v218, v179, s4, v236
	v_rcp_f32_e32 v205, v205
	v_exp_f32_e32 v219, v219
	v_exp_f32_e32 v218, v218
	s_nop 0
	v_rcp_f32_e32 v225, v204
	v_mul_f32_e32 v204, v204, v205
	v_add_f32_e32 v205, 1.0, v219
	v_add_f32_e32 v218, 1.0, v218
	s_nop 0
	v_med3_f32 v220, v172, s4, v236
	v_rcp_f32_e32 v218, v218
	v_exp_f32_e32 v220, v220
	v_med3_f32 v219, v164, s4, v236
	v_exp_f32_e32 v219, v219
	v_rcp_f32_e32 v226, v205
	v_mul_f32_e32 v205, v205, v218
	v_add_f32_e32 v218, 1.0, v220
	s_nop 0
	v_add_f32_e32 v219, 1.0, v219
	v_med3_f32 v220, v165, s4, v236
	v_rcp_f32_e32 v219, v219
	v_exp_f32_e32 v220, v220
	s_nop 0
	v_med3_f32 v221, v173, s4, v236
	v_exp_f32_e32 v221, v221
	v_mul_f32_e32 v222, v218, v219
	v_add_f32_e32 v219, 1.0, v220
	s_nop 0
	v_med3_f32 v220, v166, s4, v236
	v_rcp_f32_e32 v219, v219
	v_exp_f32_e32 v220, v220
	v_rcp_f32_e32 v228, v218
	v_add_f32_e32 v218, 1.0, v221
	s_nop 0
	v_med3_f32 v221, v174, s4, v236
	v_exp_f32_e32 v221, v221
	v_mul_f32_e32 v223, v218, v219
	v_add_f32_e32 v219, 1.0, v220
	s_nop 0
	v_med3_f32 v220, v167, s4, v236
	v_exp_f32_e32 v220, v220
	v_rcp_f32_e32 v230, v218
	v_add_f32_e32 v218, 1.0, v221
	s_nop 0
	v_med3_f32 v221, v175, s4, v236
	v_rcp_f32_e32 v219, v219
	v_exp_f32_e32 v221, v221
	v_add_f32_e32 v220, 1.0, v220
	v_rcp_f32_e32 v220, v220
	v_rcp_f32_e32 v232, v218
	v_mul_f32_e32 v233, v218, v219
	v_add_f32_e32 v218, 1.0, v221
	v_readlane_b32 s10, v250, 53
	v_rcp_f32_e32 v234, v218
	v_mul_f32_e32 v221, v218, v220
	v_cvt_pk_bf16_f32 v218, v198, v199
	v_lshlrev_b64 v[198:199], 11, v[200:201]
	v_readlane_b32 s11, v250, 54
	v_cvt_pk_bf16_f32 v219, v204, v205
	v_cvt_pk_bf16_f32 v220, v222, v223
	v_lshl_add_u64 v[204:205], s[74:75], 0, v[198:199]
	v_lshlrev_b64 v[222:223], 1, v[14:15]
	v_lshl_add_u64 v[198:199], s[10:11], 0, v[198:199]
	v_cvt_pk_bf16_f32 v221, v233, v221
	v_lshl_add_u64 v[204:205], v[204:205], 0, v[222:223]
	v_lshl_add_u64 v[198:199], v[198:199], 0, v[222:223]
	s_mov_b64 s[10:11], 0
	global_store_dwordx4 v[204:205], v[218:221], off
	s_nop 1
	v_cvt_pk_bf16_f32 v218, v217, v224
	v_cvt_pk_bf16_f32 v219, v225, v226
	v_cvt_pk_bf16_f32 v220, v228, v230
	v_cvt_pk_bf16_f32 v221, v232, v234
	global_store_dwordx4 v[198:199], v[218:221], off

.LBB0_454:
	v_mov_b32_e32 v218, v204
	v_mov_b32_e32 v219, v204
	v_cndmask_b32_e64 v217, 0, 1, s[92:93]
	v_pk_fma_f32 v[178:179], v[122:123], v[218:219], v[178:179]
	v_pk_fma_f32 v[176:177], v[120:121], v[204:205], v[176:177]
	v_or_b32_e32 v204, 16, v200
	v_mov_b32_e32 v205, v201
	v_cmp_ne_u32_e64 s[42:43], 1, v217
	s_andn2_b64 vcc, exec, s[92:93]
	s_mov_b64 s[10:11], -1
	v_readlane_b32 s30, v250, 59
	v_readlane_b32 s83, v250, 61
	v_readlane_b32 s17, v250, 63
	v_readlane_b32 s92, v251, 1
	v_readlane_b32 s93, v250, 57
	s_cbranch_vccnz .LBB0_464
	s_andn2_b64 vcc, exec, s[24:25]
	s_cbranch_vccnz .LBB0_457
	s_nop 0
	s_mov_b32 s4, 0xc22c0000
	v_med3_f32 v217, v176, s4, v236
	s_nop 0
	v_exp_f32_e32 v217, v217
	v_med3_f32 v219, v177, s4, v236
	v_exp_f32_e32 v219, v219
	s_nop 0
	v_med3_f32 v218, v168, s4, v236
	s_nop 0
	v_exp_f32_e32 v218, v218
	v_add_f32_e32 v217, 1.0, v217
	v_med3_f32 v220, v169, s4, v236
	s_nop 0
	v_rcp_f32_e32 v217, v217
	v_exp_f32_e32 v220, v220
	v_add_f32_e32 v219, 1.0, v219
	v_med3_f32 v221, v170, s4, v236
	v_rcp_f32_e32 v219, v219
	v_exp_f32_e32 v221, v221
	v_add_f32_e32 v218, 1.0, v218
	v_rcp_f32_e32 v226, v218
	v_mul_f32_e32 v217, v218, v217
	v_add_f32_e32 v218, 1.0, v220
	s_nop 0
	v_rcp_f32_e32 v228, v218
	v_med3_f32 v220, v178, s4, v236
	v_mul_f32_e32 v218, v218, v219
	v_add_f32_e32 v219, 1.0, v221
	s_nop 0
	v_exp_f32_e32 v220, v220
	v_med3_f32 v221, v179, s4, v236
	v_exp_f32_e32 v221, v221
	s_nop 0
	v_add_f32_e32 v220, 1.0, v220
	v_med3_f32 v222, v171, s4, v236
	s_nop 0
	v_rcp_f32_e32 v220, v220
	v_exp_f32_e32 v222, v222
	v_add_f32_e32 v221, 1.0, v221
	v_med3_f32 v223, v172, s4, v236
	v_rcp_f32_e32 v221, v221
	v_exp_f32_e32 v223, v223
	v_rcp_f32_e32 v230, v219
	v_mul_f32_e32 v219, v219, v220
	v_add_f32_e32 v220, 1.0, v222
	s_nop 0
	v_rcp_f32_e32 v234, v220
	v_med3_f32 v222, v164, s4, v236
	v_mul_f32_e32 v220, v220, v221
	v_add_f32_e32 v221, 1.0, v223
	s_nop 0
	v_exp_f32_e32 v222, v222
	v_med3_f32 v223, v165, s4, v236
	v_exp_f32_e32 v223, v223
	s_nop 0
	v_add_f32_e32 v222, 1.0, v222
	v_med3_f32 v224, v173, s4, v236
	s_nop 0
	v_rcp_f32_e32 v222, v222
	v_exp_f32_e32 v224, v224
	v_add_f32_e32 v223, 1.0, v223
	v_med3_f32 v225, v174, s4, v236
	v_rcp_f32_e32 v223, v223
	v_exp_f32_e32 v225, v225
	v_rcp_f32_e32 v235, v221
	v_mul_f32_e32 v221, v221, v222
	v_add_f32_e32 v222, 1.0, v224
	s_nop 0
	v_rcp_f32_e32 v237, v222
	v_med3_f32 v224, v166, s4, v236
	v_mul_f32_e32 v222, v222, v223
	v_add_f32_e32 v223, 1.0, v225
	s_nop 0
	v_exp_f32_e32 v224, v224
	v_med3_f32 v225, v167, s4, v236
	v_exp_f32_e32 v225, v225
	s_nop 0
	v_add_f32_e32 v224, 1.0, v224
	v_med3_f32 v232, v175, s4, v236
	v_rcp_f32_e32 v224, v224
	v_exp_f32_e32 v232, v232
	v_add_f32_e32 v225, 1.0, v225
	v_rcp_f32_e32 v225, v225
	v_rcp_f32_e32 v238, v223
	v_mul_f32_e32 v223, v223, v224
	v_add_f32_e32 v224, 1.0, v232
	v_readlane_b32 s10, v250, 53
	v_rcp_f32_e32 v239, v224
	v_mul_f32_e32 v224, v224, v225
	v_cvt_pk_bf16_f32 v218, v217, v218
	v_cvt_pk_bf16_f32 v219, v219, v220
	v_cvt_pk_bf16_f32 v220, v221, v222
	v_cvt_pk_bf16_f32 v221, v223, v224
	v_lshlrev_b64 v[222:223], 11, v[204:205]
	v_readlane_b32 s11, v250, 54
	v_lshl_add_u64 v[224:225], s[74:75], 0, v[222:223]
	v_lshlrev_b64 v[232:233], 1, v[14:15]
	v_lshl_add_u64 v[222:223], s[10:11], 0, v[222:223]
	v_lshl_add_u64 v[224:225], v[224:225], 0, v[232:233]
	v_lshl_add_u64 v[222:223], v[222:223], 0, v[232:233]
	s_mov_b64 s[10:11], 0
	global_store_dwordx4 v[224:225], v[218:221], off
	s_nop 1
	v_cvt_pk_bf16_f32 v218, v226, v228
	v_cvt_pk_bf16_f32 v219, v230, v234
	v_cvt_pk_bf16_f32 v220, v235, v237
	v_cvt_pk_bf16_f32 v221, v238, v239
	global_store_dwordx4 v[222:223], v[218:221], off

.LBB0_474:
	v_mov_b32_e32 v218, v204
	v_mov_b32_e32 v219, v204
	v_pk_fma_f32 v[178:179], v[114:115], v[218:219], v[178:179]
	v_pk_fma_f32 v[176:177], v[112:113], v[204:205], v[176:177]
	v_or_b32_e32 v204, 32, v200
	v_mov_b32_e32 v205, v201
	s_and_b64 vcc, exec, s[42:43]
	s_mov_b64 s[10:11], -1
	s_cbranch_vccnz .LBB0_484
	s_andn2_b64 vcc, exec, s[24:25]
	s_cbranch_vccnz .LBB0_477
	s_nop 0
	s_mov_b32 s4, 0xc22c0000
	v_med3_f32 v217, v176, s4, v236
	s_nop 0
	v_exp_f32_e32 v217, v217
	v_med3_f32 v219, v177, s4, v236
	v_exp_f32_e32 v219, v219
	s_nop 0
	v_med3_f32 v218, v168, s4, v236
	s_nop 0
	v_exp_f32_e32 v218, v218
	v_add_f32_e32 v217, 1.0, v217
	v_med3_f32 v220, v169, s4, v236
	s_nop 0
	v_rcp_f32_e32 v217, v217
	v_exp_f32_e32 v220, v220
	v_add_f32_e32 v219, 1.0, v219
	v_med3_f32 v221, v170, s4, v236
	v_rcp_f32_e32 v219, v219
	v_exp_f32_e32 v221, v221
	v_add_f32_e32 v218, 1.0, v218
	v_rcp_f32_e32 v226, v218
	v_mul_f32_e32 v217, v218, v217
	v_add_f32_e32 v218, 1.0, v220
	s_nop 0
	v_rcp_f32_e32 v228, v218
	v_med3_f32 v220, v178, s4, v236
	v_mul_f32_e32 v218, v218, v219
	v_add_f32_e32 v219, 1.0, v221
	s_nop 0
	v_exp_f32_e32 v220, v220
	v_med3_f32 v221, v179, s4, v236
	v_exp_f32_e32 v221, v221
	s_nop 0
	v_add_f32_e32 v220, 1.0, v220
	v_med3_f32 v222, v171, s4, v236
	s_nop 0
	v_rcp_f32_e32 v220, v220
	v_exp_f32_e32 v222, v222
	v_add_f32_e32 v221, 1.0, v221
	v_med3_f32 v223, v172, s4, v236
	v_rcp_f32_e32 v221, v221
	v_exp_f32_e32 v223, v223
	v_rcp_f32_e32 v230, v219
	v_mul_f32_e32 v219, v219, v220
	v_add_f32_e32 v220, 1.0, v222
	s_nop 0
	v_rcp_f32_e32 v234, v220
	v_med3_f32 v222, v164, s4, v236
	v_mul_f32_e32 v220, v220, v221
	v_add_f32_e32 v221, 1.0, v223
	s_nop 0
	v_exp_f32_e32 v222, v222
	v_med3_f32 v223, v165, s4, v236
	v_exp_f32_e32 v223, v223
	s_nop 0
	v_add_f32_e32 v222, 1.0, v222
	v_med3_f32 v224, v173, s4, v236
	s_nop 0
	v_rcp_f32_e32 v222, v222
	v_exp_f32_e32 v224, v224
	v_add_f32_e32 v223, 1.0, v223
	v_med3_f32 v225, v174, s4, v236
	v_rcp_f32_e32 v223, v223
	v_exp_f32_e32 v225, v225
	v_rcp_f32_e32 v235, v221
	v_mul_f32_e32 v221, v221, v222
	v_add_f32_e32 v222, 1.0, v224
	s_nop 0
	v_rcp_f32_e32 v237, v222
	v_med3_f32 v224, v166, s4, v236
	v_mul_f32_e32 v222, v222, v223
	v_add_f32_e32 v223, 1.0, v225
	s_nop 0
	v_exp_f32_e32 v224, v224
	v_med3_f32 v225, v167, s4, v236
	v_exp_f32_e32 v225, v225
	s_nop 0
	v_add_f32_e32 v224, 1.0, v224
	v_med3_f32 v232, v175, s4, v236
	v_rcp_f32_e32 v224, v224
	v_exp_f32_e32 v232, v232
	v_add_f32_e32 v225, 1.0, v225
	v_rcp_f32_e32 v225, v225
	v_rcp_f32_e32 v238, v223
	v_mul_f32_e32 v223, v223, v224
	v_add_f32_e32 v224, 1.0, v232
	v_readlane_b32 s4, v250, 53
	v_rcp_f32_e32 v239, v224
	v_mul_f32_e32 v224, v224, v225
	v_cvt_pk_bf16_f32 v218, v217, v218
	v_cvt_pk_bf16_f32 v219, v219, v220
	v_cvt_pk_bf16_f32 v220, v221, v222
	v_cvt_pk_bf16_f32 v221, v223, v224
	v_lshlrev_b64 v[222:223], 11, v[204:205]
	v_readlane_b32 s5, v250, 54
	v_lshl_add_u64 v[224:225], s[74:75], 0, v[222:223]
	v_lshlrev_b64 v[232:233], 1, v[14:15]
	v_lshl_add_u64 v[222:223], s[4:5], 0, v[222:223]
	v_lshl_add_u64 v[224:225], v[224:225], 0, v[232:233]
	v_lshl_add_u64 v[222:223], v[222:223], 0, v[232:233]
	s_mov_b64 s[10:11], 0
	global_store_dwordx4 v[224:225], v[218:221], off
	s_nop 1
	v_cvt_pk_bf16_f32 v218, v226, v228
	v_cvt_pk_bf16_f32 v219, v230, v234
	v_cvt_pk_bf16_f32 v220, v235, v237
	v_cvt_pk_bf16_f32 v221, v238, v239
	global_store_dwordx4 v[222:223], v[218:221], off

.LBB0_494:
	v_mov_b32_e32 v218, v204
	v_mov_b32_e32 v219, v204
	v_pk_fma_f32 v[178:179], v[106:107], v[218:219], v[178:179]
	v_pk_fma_f32 v[176:177], v[104:105], v[204:205], v[176:177]
	v_or_b32_e32 v204, 48, v200
	v_mov_b32_e32 v205, v201
	s_and_b64 vcc, exec, s[42:43]
	s_mov_b64 s[10:11], -1
	s_cbranch_vccnz .LBB0_504
	s_andn2_b64 vcc, exec, s[24:25]
	s_cbranch_vccnz .LBB0_497
	s_nop 0
	s_mov_b32 s4, 0xc22c0000
	v_med3_f32 v217, v176, s4, v236
	s_nop 0
	v_exp_f32_e32 v217, v217
	v_med3_f32 v219, v177, s4, v236
	v_exp_f32_e32 v219, v219
	s_nop 0
	v_med3_f32 v218, v168, s4, v236
	s_nop 0
	v_exp_f32_e32 v218, v218
	v_add_f32_e32 v217, 1.0, v217
	v_med3_f32 v220, v169, s4, v236
	s_nop 0
	v_rcp_f32_e32 v217, v217
	v_exp_f32_e32 v220, v220
	v_add_f32_e32 v219, 1.0, v219
	v_med3_f32 v221, v170, s4, v236
	v_rcp_f32_e32 v219, v219
	v_exp_f32_e32 v221, v221
	v_add_f32_e32 v218, 1.0, v218
	v_rcp_f32_e32 v226, v218
	v_mul_f32_e32 v217, v218, v217
	v_add_f32_e32 v218, 1.0, v220
	s_nop 0
	v_rcp_f32_e32 v228, v218
	v_med3_f32 v220, v178, s4, v236
	v_mul_f32_e32 v218, v218, v219
	v_add_f32_e32 v219, 1.0, v221
	s_nop 0
	v_exp_f32_e32 v220, v220
	v_med3_f32 v221, v179, s4, v236
	v_exp_f32_e32 v221, v221
	s_nop 0
	v_add_f32_e32 v220, 1.0, v220
	v_med3_f32 v222, v171, s4, v236
	s_nop 0
	v_rcp_f32_e32 v220, v220
	v_exp_f32_e32 v222, v222
	v_add_f32_e32 v221, 1.0, v221
	v_med3_f32 v223, v172, s4, v236
	v_rcp_f32_e32 v221, v221
	v_exp_f32_e32 v223, v223
	v_rcp_f32_e32 v230, v219
	v_mul_f32_e32 v219, v219, v220
	v_add_f32_e32 v220, 1.0, v222
	s_nop 0
	v_rcp_f32_e32 v234, v220
	v_med3_f32 v222, v164, s4, v236
	v_mul_f32_e32 v220, v220, v221
	v_add_f32_e32 v221, 1.0, v223
	s_nop 0
	v_exp_f32_e32 v222, v222
	v_med3_f32 v223, v165, s4, v236
	v_exp_f32_e32 v223, v223
	s_nop 0
	v_add_f32_e32 v222, 1.0, v222
	v_med3_f32 v224, v173, s4, v236
	s_nop 0
	v_rcp_f32_e32 v222, v222
	v_exp_f32_e32 v224, v224
	v_add_f32_e32 v223, 1.0, v223
	v_med3_f32 v225, v174, s4, v236
	v_rcp_f32_e32 v223, v223
	v_exp_f32_e32 v225, v225
	v_rcp_f32_e32 v235, v221
	v_mul_f32_e32 v221, v221, v222
	v_add_f32_e32 v222, 1.0, v224
	s_nop 0
	v_rcp_f32_e32 v237, v222
	v_med3_f32 v224, v166, s4, v236
	v_mul_f32_e32 v222, v222, v223
	v_add_f32_e32 v223, 1.0, v225
	s_nop 0
	v_exp_f32_e32 v224, v224
	v_med3_f32 v225, v167, s4, v236
	v_exp_f32_e32 v225, v225
	s_nop 0
	v_add_f32_e32 v224, 1.0, v224
	v_med3_f32 v232, v175, s4, v236
	v_rcp_f32_e32 v224, v224
	v_exp_f32_e32 v232, v232
	v_add_f32_e32 v225, 1.0, v225
	v_rcp_f32_e32 v225, v225
	v_rcp_f32_e32 v238, v223
	v_mul_f32_e32 v223, v223, v224
	v_add_f32_e32 v224, 1.0, v232
	v_readlane_b32 s4, v250, 53
	v_rcp_f32_e32 v239, v224
	v_mul_f32_e32 v224, v224, v225
	v_cvt_pk_bf16_f32 v218, v217, v218
	v_cvt_pk_bf16_f32 v219, v219, v220
	v_cvt_pk_bf16_f32 v220, v221, v222
	v_cvt_pk_bf16_f32 v221, v223, v224
	v_lshlrev_b64 v[222:223], 11, v[204:205]
	v_readlane_b32 s5, v250, 54
	v_lshl_add_u64 v[224:225], s[74:75], 0, v[222:223]
	v_lshlrev_b64 v[232:233], 1, v[14:15]
	v_lshl_add_u64 v[222:223], s[4:5], 0, v[222:223]
	v_lshl_add_u64 v[224:225], v[224:225], 0, v[232:233]
	v_lshl_add_u64 v[222:223], v[222:223], 0, v[232:233]
	s_mov_b64 s[10:11], 0
	global_store_dwordx4 v[224:225], v[218:221], off
	s_nop 1
	v_cvt_pk_bf16_f32 v218, v226, v228
	v_cvt_pk_bf16_f32 v219, v230, v234
	v_cvt_pk_bf16_f32 v220, v235, v237
	v_cvt_pk_bf16_f32 v221, v238, v239
	global_store_dwordx4 v[222:223], v[218:221], off

.LBB0_514:
	v_mov_b32_e32 v218, v204
	v_mov_b32_e32 v219, v204
	v_pk_fma_f32 v[178:179], v[66:67], v[218:219], v[178:179]
	v_pk_fma_f32 v[176:177], v[64:65], v[204:205], v[176:177]
	v_lshl_add_u64 v[204:205], v[200:201], 0, s[34:35]
	s_and_b64 vcc, exec, s[42:43]
	s_mov_b64 s[10:11], -1
	s_cbranch_vccnz .LBB0_524
	s_andn2_b64 vcc, exec, s[24:25]
	s_cbranch_vccnz .LBB0_517
	s_nop 0
	s_mov_b32 s4, 0xc22c0000
	v_med3_f32 v217, v176, s4, v236
	s_nop 0
	v_exp_f32_e32 v217, v217
	v_med3_f32 v219, v177, s4, v236
	v_exp_f32_e32 v219, v219
	s_nop 0
	v_med3_f32 v218, v168, s4, v236
	s_nop 0
	v_exp_f32_e32 v218, v218
	v_add_f32_e32 v217, 1.0, v217
	v_med3_f32 v220, v169, s4, v236
	s_nop 0
	v_rcp_f32_e32 v217, v217
	v_exp_f32_e32 v220, v220
	v_add_f32_e32 v219, 1.0, v219
	v_med3_f32 v221, v170, s4, v236
	v_rcp_f32_e32 v219, v219
	v_exp_f32_e32 v221, v221
	v_add_f32_e32 v218, 1.0, v218
	v_rcp_f32_e32 v226, v218
	v_mul_f32_e32 v217, v218, v217
	v_add_f32_e32 v218, 1.0, v220
	s_nop 0
	v_rcp_f32_e32 v228, v218
	v_med3_f32 v220, v178, s4, v236
	v_mul_f32_e32 v218, v218, v219
	v_add_f32_e32 v219, 1.0, v221
	s_nop 0
	v_exp_f32_e32 v220, v220
	v_med3_f32 v221, v179, s4, v236
	v_exp_f32_e32 v221, v221
	s_nop 0
	v_add_f32_e32 v220, 1.0, v220
	v_med3_f32 v222, v171, s4, v236
	s_nop 0
	v_rcp_f32_e32 v220, v220
	v_exp_f32_e32 v222, v222
	v_add_f32_e32 v221, 1.0, v221
	v_med3_f32 v223, v172, s4, v236
	v_rcp_f32_e32 v221, v221
	v_exp_f32_e32 v223, v223
	v_rcp_f32_e32 v230, v219
	v_mul_f32_e32 v219, v219, v220
	v_add_f32_e32 v220, 1.0, v222
	s_nop 0
	v_rcp_f32_e32 v234, v220
	v_med3_f32 v222, v164, s4, v236
	v_mul_f32_e32 v220, v220, v221
	v_add_f32_e32 v221, 1.0, v223
	s_nop 0
	v_exp_f32_e32 v222, v222
	v_med3_f32 v223, v165, s4, v236
	v_exp_f32_e32 v223, v223
	s_nop 0
	v_add_f32_e32 v222, 1.0, v222
	v_med3_f32 v224, v173, s4, v236
	s_nop 0
	v_rcp_f32_e32 v222, v222
	v_exp_f32_e32 v224, v224
	v_add_f32_e32 v223, 1.0, v223
	v_med3_f32 v225, v174, s4, v236
	v_rcp_f32_e32 v223, v223
	v_exp_f32_e32 v225, v225
	v_rcp_f32_e32 v235, v221
	v_mul_f32_e32 v221, v221, v222
	v_add_f32_e32 v222, 1.0, v224
	s_nop 0
	v_rcp_f32_e32 v237, v222
	v_med3_f32 v224, v166, s4, v236
	v_mul_f32_e32 v222, v222, v223
	v_add_f32_e32 v223, 1.0, v225
	s_nop 0
	v_exp_f32_e32 v224, v224
	v_med3_f32 v225, v167, s4, v236
	v_exp_f32_e32 v225, v225
	s_nop 0
	v_add_f32_e32 v224, 1.0, v224
	v_med3_f32 v232, v175, s4, v236
	v_rcp_f32_e32 v224, v224
	v_exp_f32_e32 v232, v232
	v_add_f32_e32 v225, 1.0, v225
	v_rcp_f32_e32 v225, v225
	v_rcp_f32_e32 v238, v223
	v_mul_f32_e32 v223, v223, v224
	v_add_f32_e32 v224, 1.0, v232
	v_readlane_b32 s4, v250, 53
	v_rcp_f32_e32 v239, v224
	v_mul_f32_e32 v224, v224, v225
	v_cvt_pk_bf16_f32 v218, v217, v218
	v_cvt_pk_bf16_f32 v219, v219, v220
	v_cvt_pk_bf16_f32 v220, v221, v222
	v_cvt_pk_bf16_f32 v221, v223, v224
	v_lshlrev_b64 v[222:223], 11, v[204:205]
	v_readlane_b32 s5, v250, 54
	v_lshl_add_u64 v[224:225], s[74:75], 0, v[222:223]
	v_lshlrev_b64 v[232:233], 1, v[14:15]
	v_lshl_add_u64 v[222:223], s[4:5], 0, v[222:223]
	v_lshl_add_u64 v[224:225], v[224:225], 0, v[232:233]
	v_lshl_add_u64 v[222:223], v[222:223], 0, v[232:233]
	s_mov_b64 s[10:11], 0
	global_store_dwordx4 v[224:225], v[218:221], off
	s_nop 1
	v_cvt_pk_bf16_f32 v218, v226, v228
	v_cvt_pk_bf16_f32 v219, v230, v234
	v_cvt_pk_bf16_f32 v220, v235, v237
	v_cvt_pk_bf16_f32 v221, v238, v239
	global_store_dwordx4 v[222:223], v[218:221], off

.LBB0_534:
	v_mov_b32_e32 v218, v204
	v_mov_b32_e32 v219, v204
	s_mov_b64 s[4:5], 0x90
	v_pk_fma_f32 v[178:179], v[58:59], v[218:219], v[178:179]
	v_pk_fma_f32 v[176:177], v[56:57], v[204:205], v[176:177]
	v_lshl_add_u64 v[204:205], v[200:201], 0, s[4:5]
	s_and_b64 vcc, exec, s[42:43]
	s_mov_b64 s[10:11], -1
	s_cbranch_vccnz .LBB0_544
	s_andn2_b64 vcc, exec, s[24:25]
	s_cbranch_vccnz .LBB0_537
	s_nop 0
	s_mov_b32 s4, 0xc22c0000
	v_med3_f32 v217, v176, s4, v236
	s_nop 0
	v_exp_f32_e32 v217, v217
	v_med3_f32 v219, v177, s4, v236
	v_exp_f32_e32 v219, v219
	s_nop 0
	v_med3_f32 v218, v168, s4, v236
	s_nop 0
	v_exp_f32_e32 v218, v218
	v_add_f32_e32 v217, 1.0, v217
	v_med3_f32 v220, v169, s4, v236
	s_nop 0
	v_rcp_f32_e32 v217, v217
	v_exp_f32_e32 v220, v220
	v_add_f32_e32 v219, 1.0, v219
	v_med3_f32 v221, v170, s4, v236
	v_rcp_f32_e32 v219, v219
	v_exp_f32_e32 v221, v221
	v_add_f32_e32 v218, 1.0, v218
	v_rcp_f32_e32 v226, v218
	v_mul_f32_e32 v217, v218, v217
	v_add_f32_e32 v218, 1.0, v220
	s_nop 0
	v_rcp_f32_e32 v228, v218
	v_med3_f32 v220, v178, s4, v236
	v_mul_f32_e32 v218, v218, v219
	v_add_f32_e32 v219, 1.0, v221
	s_nop 0
	v_exp_f32_e32 v220, v220
	v_med3_f32 v221, v179, s4, v236
	v_exp_f32_e32 v221, v221
	s_nop 0
	v_add_f32_e32 v220, 1.0, v220
	v_med3_f32 v222, v171, s4, v236
	s_nop 0
	v_rcp_f32_e32 v220, v220
	v_exp_f32_e32 v222, v222
	v_add_f32_e32 v221, 1.0, v221
	v_med3_f32 v223, v172, s4, v236
	v_rcp_f32_e32 v221, v221
	v_exp_f32_e32 v223, v223
	v_rcp_f32_e32 v230, v219
	v_mul_f32_e32 v219, v219, v220
	v_add_f32_e32 v220, 1.0, v222
	s_nop 0
	v_rcp_f32_e32 v234, v220
	v_med3_f32 v222, v164, s4, v236
	v_mul_f32_e32 v220, v220, v221
	v_add_f32_e32 v221, 1.0, v223
	s_nop 0
	v_exp_f32_e32 v222, v222
	v_med3_f32 v223, v165, s4, v236
	v_exp_f32_e32 v223, v223
	s_nop 0
	v_add_f32_e32 v222, 1.0, v222
	v_med3_f32 v224, v173, s4, v236
	s_nop 0
	v_rcp_f32_e32 v222, v222
	v_exp_f32_e32 v224, v224
	v_add_f32_e32 v223, 1.0, v223
	v_med3_f32 v225, v174, s4, v236
	v_rcp_f32_e32 v223, v223
	v_exp_f32_e32 v225, v225
	v_rcp_f32_e32 v235, v221
	v_mul_f32_e32 v221, v221, v222
	v_add_f32_e32 v222, 1.0, v224
	s_nop 0
	v_rcp_f32_e32 v237, v222
	v_med3_f32 v224, v166, s4, v236
	v_mul_f32_e32 v222, v222, v223
	v_add_f32_e32 v223, 1.0, v225
	s_nop 0
	v_exp_f32_e32 v224, v224
	v_med3_f32 v225, v167, s4, v236
	v_exp_f32_e32 v225, v225
	s_nop 0
	v_add_f32_e32 v224, 1.0, v224
	v_med3_f32 v232, v175, s4, v236
	v_rcp_f32_e32 v224, v224
	v_exp_f32_e32 v232, v232
	v_add_f32_e32 v225, 1.0, v225
	v_rcp_f32_e32 v225, v225
	v_rcp_f32_e32 v238, v223
	v_mul_f32_e32 v223, v223, v224
	v_add_f32_e32 v224, 1.0, v232
	v_readlane_b32 s4, v250, 53
	v_rcp_f32_e32 v239, v224
	v_mul_f32_e32 v224, v224, v225
	v_cvt_pk_bf16_f32 v218, v217, v218
	v_cvt_pk_bf16_f32 v219, v219, v220
	v_cvt_pk_bf16_f32 v220, v221, v222
	v_cvt_pk_bf16_f32 v221, v223, v224
	v_lshlrev_b64 v[222:223], 11, v[204:205]
	v_readlane_b32 s5, v250, 54
	v_lshl_add_u64 v[224:225], s[74:75], 0, v[222:223]
	v_lshlrev_b64 v[232:233], 1, v[14:15]
	v_lshl_add_u64 v[222:223], s[4:5], 0, v[222:223]
	v_lshl_add_u64 v[224:225], v[224:225], 0, v[232:233]
	v_lshl_add_u64 v[222:223], v[222:223], 0, v[232:233]
	s_mov_b64 s[10:11], 0
	global_store_dwordx4 v[224:225], v[218:221], off
	s_nop 1
	v_cvt_pk_bf16_f32 v218, v226, v228
	v_cvt_pk_bf16_f32 v219, v230, v234
	v_cvt_pk_bf16_f32 v220, v235, v237
	v_cvt_pk_bf16_f32 v221, v238, v239
	global_store_dwordx4 v[222:223], v[218:221], off

.LBB0_554:
	v_mov_b32_e32 v202, v204
	v_mov_b32_e32 v203, v204
	s_mov_b64 s[4:5], 0xa0
	v_pk_fma_f32 v[178:179], v[50:51], v[202:203], v[178:179]
	v_pk_fma_f32 v[176:177], v[48:49], v[204:205], v[176:177]
	v_lshl_add_u64 v[202:203], v[200:201], 0, s[4:5]
	s_and_b64 vcc, exec, s[42:43]
	s_mov_b64 s[10:11], -1
	s_cbranch_vccnz .LBB0_564
	s_andn2_b64 vcc, exec, s[24:25]
	s_cbranch_vccnz .LBB0_557
	s_nop 0
	s_mov_b32 s4, 0xc22c0000
	v_med3_f32 v204, v176, s4, v236
	s_nop 0
	v_exp_f32_e32 v204, v204
	v_med3_f32 v218, v177, s4, v236
	v_exp_f32_e32 v218, v218
	s_nop 0
	v_med3_f32 v205, v168, s4, v236
	s_nop 0
	v_exp_f32_e32 v205, v205
	v_add_f32_e32 v204, 1.0, v204
	v_med3_f32 v219, v169, s4, v236
	s_nop 0
	v_rcp_f32_e32 v204, v204
	v_exp_f32_e32 v219, v219
	v_add_f32_e32 v218, 1.0, v218
	v_med3_f32 v220, v170, s4, v236
	v_rcp_f32_e32 v218, v218
	v_exp_f32_e32 v220, v220
	v_add_f32_e32 v205, 1.0, v205
	v_rcp_f32_e32 v217, v205
	v_mul_f32_e32 v204, v205, v204
	v_add_f32_e32 v205, 1.0, v219
	s_nop 0
	v_rcp_f32_e32 v226, v205
	v_med3_f32 v219, v178, s4, v236
	v_mul_f32_e32 v205, v205, v218
	v_add_f32_e32 v218, 1.0, v220
	s_nop 0
	v_exp_f32_e32 v219, v219
	v_med3_f32 v220, v179, s4, v236
	v_exp_f32_e32 v220, v220
	s_nop 0
	v_add_f32_e32 v219, 1.0, v219
	v_med3_f32 v221, v171, s4, v236
	s_nop 0
	v_rcp_f32_e32 v219, v219
	v_exp_f32_e32 v221, v221
	v_add_f32_e32 v220, 1.0, v220
	v_med3_f32 v222, v172, s4, v236
	v_rcp_f32_e32 v220, v220
	v_exp_f32_e32 v222, v222
	v_rcp_f32_e32 v228, v218
	v_mul_f32_e32 v219, v218, v219
	v_add_f32_e32 v218, 1.0, v221
	s_nop 0
	v_rcp_f32_e32 v230, v218
	v_med3_f32 v221, v164, s4, v236
	v_mul_f32_e32 v220, v218, v220
	v_add_f32_e32 v218, 1.0, v222
	s_nop 0
	v_exp_f32_e32 v221, v221
	v_med3_f32 v222, v165, s4, v236
	v_exp_f32_e32 v222, v222
	s_nop 0
	v_add_f32_e32 v221, 1.0, v221
	v_med3_f32 v223, v173, s4, v236
	s_nop 0
	v_rcp_f32_e32 v221, v221
	v_exp_f32_e32 v223, v223
	v_add_f32_e32 v222, 1.0, v222
	v_med3_f32 v224, v174, s4, v236
	v_rcp_f32_e32 v222, v222
	v_exp_f32_e32 v224, v224
	v_rcp_f32_e32 v232, v218
	v_mul_f32_e32 v221, v218, v221
	v_add_f32_e32 v218, 1.0, v223
	s_nop 0
	v_rcp_f32_e32 v233, v218
	v_med3_f32 v223, v166, s4, v236
	v_mul_f32_e32 v222, v218, v222
	v_add_f32_e32 v218, 1.0, v224
	s_nop 0
	v_exp_f32_e32 v223, v223
	v_med3_f32 v224, v167, s4, v236
	v_exp_f32_e32 v224, v224
	s_nop 0
	v_add_f32_e32 v223, 1.0, v223
	v_med3_f32 v225, v175, s4, v236
	v_rcp_f32_e32 v223, v223
	v_exp_f32_e32 v225, v225
	v_add_f32_e32 v224, 1.0, v224
	v_rcp_f32_e32 v224, v224
	v_rcp_f32_e32 v234, v218
	v_mul_f32_e32 v223, v218, v223
	v_add_f32_e32 v218, 1.0, v225
	v_readlane_b32 s4, v250, 53
	v_rcp_f32_e32 v235, v218
	v_mul_f32_e32 v224, v218, v224
	v_cvt_pk_bf16_f32 v218, v204, v205
	v_lshlrev_b64 v[204:205], 11, v[202:203]
	v_readlane_b32 s5, v250, 54
	v_cvt_pk_bf16_f32 v219, v219, v220
	v_cvt_pk_bf16_f32 v220, v221, v222
	v_cvt_pk_bf16_f32 v221, v223, v224
	v_lshl_add_u64 v[222:223], s[74:75], 0, v[204:205]
	v_lshlrev_b64 v[224:225], 1, v[14:15]
	v_lshl_add_u64 v[204:205], s[4:5], 0, v[204:205]
	v_lshl_add_u64 v[222:223], v[222:223], 0, v[224:225]
	v_lshl_add_u64 v[204:205], v[204:205], 0, v[224:225]
	s_mov_b64 s[10:11], 0
	global_store_dwordx4 v[222:223], v[218:221], off
	s_nop 1
	v_cvt_pk_bf16_f32 v218, v217, v226
	v_cvt_pk_bf16_f32 v219, v228, v230
	v_cvt_pk_bf16_f32 v220, v232, v233
	v_cvt_pk_bf16_f32 v221, v234, v235
	global_store_dwordx4 v[204:205], v[218:221], off

.LBB0_574:
	s_mov_b64 s[4:5], 0xb0
	s_waitcnt vmcnt(0)
	v_mov_b32_e32 v148, v202
	v_mov_b32_e32 v149, v202
	v_lshl_add_u64 v[152:153], v[200:201], 0, s[4:5]
	v_pk_fma_f32 v[150:151], v[42:43], v[148:149], v[178:179]
	v_pk_fma_f32 v[148:149], v[40:41], v[202:203], v[176:177]
	s_and_b64 vcc, exec, s[42:43]
	s_mov_b64 s[10:11], -1
	s_cbranch_vccnz .LBB0_584
	s_andn2_b64 vcc, exec, s[24:25]
	s_cbranch_vccnz .LBB0_577
	s_nop 0
	s_mov_b32 s4, 0xc22c0000
	v_med3_f32 v154, v148, s4, v236
	s_nop 0
	v_exp_f32_e32 v154, v154
	v_med3_f32 v156, v149, s4, v236
	v_exp_f32_e32 v156, v156
	s_nop 0
	v_med3_f32 v155, v168, s4, v236
	s_nop 0
	v_exp_f32_e32 v155, v155
	v_add_f32_e32 v154, 1.0, v154
	v_med3_f32 v157, v169, s4, v236
	s_nop 0
	v_rcp_f32_e32 v154, v154
	v_exp_f32_e32 v157, v157
	v_add_f32_e32 v156, 1.0, v156
	v_med3_f32 v158, v170, s4, v236
	v_rcp_f32_e32 v156, v156
	v_exp_f32_e32 v158, v158
	v_add_f32_e32 v155, 1.0, v155
	v_rcp_f32_e32 v176, v155
	v_mul_f32_e32 v154, v155, v154
	v_add_f32_e32 v155, 1.0, v157
	s_nop 0
	v_rcp_f32_e32 v177, v155
	v_med3_f32 v157, v150, s4, v236
	v_mul_f32_e32 v155, v155, v156
	v_add_f32_e32 v156, 1.0, v158
	s_nop 0
	v_exp_f32_e32 v157, v157
	v_med3_f32 v158, v151, s4, v236
	v_exp_f32_e32 v158, v158
	s_nop 0
	v_add_f32_e32 v157, 1.0, v157
	v_med3_f32 v159, v171, s4, v236
	s_nop 0
	v_rcp_f32_e32 v157, v157
	v_exp_f32_e32 v159, v159
	v_add_f32_e32 v158, 1.0, v158
	v_med3_f32 v160, v172, s4, v236
	v_rcp_f32_e32 v158, v158
	v_exp_f32_e32 v160, v160
	v_rcp_f32_e32 v178, v156
	v_mul_f32_e32 v156, v156, v157
	v_add_f32_e32 v157, 1.0, v159
	s_nop 0
	v_rcp_f32_e32 v179, v157
	v_med3_f32 v159, v164, s4, v236
	v_mul_f32_e32 v157, v157, v158
	v_add_f32_e32 v158, 1.0, v160
	s_nop 0
	v_exp_f32_e32 v159, v159
	v_med3_f32 v160, v165, s4, v236
	v_exp_f32_e32 v160, v160
	s_nop 0
	v_add_f32_e32 v159, 1.0, v159
	v_med3_f32 v161, v173, s4, v236
	s_nop 0
	v_rcp_f32_e32 v159, v159
	v_exp_f32_e32 v161, v161
	v_add_f32_e32 v160, 1.0, v160
	v_med3_f32 v162, v174, s4, v236
	v_rcp_f32_e32 v160, v160
	v_exp_f32_e32 v162, v162
	v_rcp_f32_e32 v196, v158
	v_mul_f32_e32 v158, v158, v159
	v_add_f32_e32 v159, 1.0, v161
	s_nop 0
	v_rcp_f32_e32 v197, v159
	v_med3_f32 v161, v166, s4, v236
	v_mul_f32_e32 v159, v159, v160
	v_add_f32_e32 v160, 1.0, v162
	s_nop 0
	v_exp_f32_e32 v161, v161
	v_med3_f32 v162, v167, s4, v236
	v_exp_f32_e32 v162, v162
	s_nop 0
	v_add_f32_e32 v161, 1.0, v161
	v_med3_f32 v163, v175, s4, v236
	v_rcp_f32_e32 v161, v161
	v_exp_f32_e32 v163, v163
	v_add_f32_e32 v162, 1.0, v162
	v_rcp_f32_e32 v162, v162
	v_rcp_f32_e32 v200, v160
	v_mul_f32_e32 v160, v160, v161
	v_add_f32_e32 v161, 1.0, v163
	v_readlane_b32 s4, v250, 53
	v_rcp_f32_e32 v201, v161
	v_mul_f32_e32 v161, v161, v162
	v_cvt_pk_bf16_f32 v154, v154, v155
	v_cvt_pk_bf16_f32 v155, v156, v157
	v_cvt_pk_bf16_f32 v156, v158, v159
	v_lshlrev_b64 v[158:159], 11, v[152:153]
	v_readlane_b32 s5, v250, 54
	v_cvt_pk_bf16_f32 v157, v160, v161
	v_lshl_add_u64 v[160:161], s[74:75], 0, v[158:159]
	v_lshlrev_b64 v[162:163], 1, v[14:15]
	v_lshl_add_u64 v[158:159], s[4:5], 0, v[158:159]
	v_lshl_add_u64 v[160:161], v[160:161], 0, v[162:163]
	v_lshl_add_u64 v[158:159], v[158:159], 0, v[162:163]
	s_mov_b64 s[10:11], 0
	global_store_dwordx4 v[160:161], v[154:157], off
	s_nop 1
	v_cvt_pk_bf16_f32 v154, v176, v177
	v_cvt_pk_bf16_f32 v155, v178, v179
	v_cvt_pk_bf16_f32 v156, v196, v197
	v_cvt_pk_bf16_f32 v157, v200, v201
	global_store_dwordx4 v[158:159], v[154:157], off
